# hand-written load-pipelined out-proj epilogue (x residual + gain loads prefetched 3 steps ahead)
# baseline (speedup 1.0000x reference)
; __device__ __forceinline__ u32x4 pack8(f32x4 a, f32x4 b) { u32x4 w; w.x = pk2(a[0], a[1]); w.y = pk2(a[2], a[3]); w.z = pk2(b[0], b[1]); w.w = pk2(b[2], b[3]); return w; }
;     __device__ __forceinline__ void operator()(const f32x4 (&acc)[2][2][4][2], const Unit& u, int wr, int wc, int fr, int fq) const {
; #pragma unroll
;         for (int ai = 0; ai < 2; ++ai)
; #pragma unroll
;             for (int m = 0; m < 4; ++m) {
;                 const int r = u.pm * 256 + ai * 128 + wr * 64 + m * 16 + fr;
;                 const float* x = r < MP ? xp + (size_t)r * 1024 : xs + (size_t)(r - MP) * 1024;
;                 float ss = 0.f;
; #pragma unroll
;                 for (int bj = 0; bj < 2; ++bj) {
;                     const int c = u.pn * 256 + 128 * bj + 32 * wc + 8 * fq;
;                     const f32x4 r0 = *(const f32x4*)(x + c), r1 = *(const f32x4*)(x + c + 4);
;                     const f32x4 y0 = r0 + acc[ai][bj][m][0], y1 = r1 + acc[ai][bj][m][1];
;                     const f32x4 g0 = *(const f32x4*)(gain + c), g1 = *(const f32x4*)(gain + c + 4);
;                     *(u32x4*)(h2 + (size_t)r * 1024 + c) = pack8(y0 * g0, y1 * g1);
;                     ss += (y0[0] * y0[0] + y0[1] * y0[1]) + (y0[2] * y0[2] + y0[3] * y0[3]) + (y1[0] * y1[0] + y1[1] * y1[1]) + (y1[2] * y1[2] + y1[3] * y1[3]);
;                 }
;                 ss += __shfl_xor(ss, 16); ss += __shfl_xor(ss, 32);
;                 if (fq == 0) atomicAdd(rowsq + r, ss);
;                 asm volatile("" ::: "memory");
;             }
;     }
.LBB0_933:
	v_lshl_add_u32 v150, s36, 8, v152
	s_lshl_b32 s35, s36, 8
	s_sub_u32 s36, s8, 0x10000000
	s_subb_u32 s37, s9, 0
	s_cmp_ge_u32 s35, 0x10000
	s_cselect_b32 s36, s36, s6
	s_cselect_b32 s37, s37, s7
	v_mov_b32_e32 v151, 0
	v_lshl_or_b32 v148, s34, 8, v154
	v_mov_b32_e32 v149, 0
	s_mov_b64 s[92:93], 0x10000
	s_mov_b64 s[94:95], 0x50000
	s_mov_b64 s[96:97], 0x8000
	s_mov_b64 s[98:99], 0x28000
	v_lshlrev_b64 v[146:147], 2, v[148:149]
	v_lshlrev_b64 v[174:175], 12, v[150:151]
	v_lshl_add_u64 v[176:177], s[10:11], 0, v[146:147]
	v_lshl_add_u64 v[174:175], s[36:37], 0, v[174:175]
	v_lshl_add_u64 v[174:175], v[174:175], 0, v[146:147]
	global_load_dwordx4 v[186:189], v[176:177], off
	global_load_dwordx4 v[190:193], v[176:177], off offset:16
	global_load_dwordx4 v[194:197], v[176:177], off offset:512
	global_load_dwordx4 v[198:201], v[176:177], off offset:528
	global_load_dwordx4 v[206:209], v[174:175], off
	global_load_dwordx4 v[210:213], v[174:175], off offset:16
	global_load_dwordx4 v[214:217], v[174:175], off offset:512
	global_load_dwordx4 v[218:221], v[174:175], off offset:528
	v_lshl_add_u64 v[174:175], v[174:175], 0, s[92:93]
	global_load_dwordx4 v[228:231], v[174:175], off
	global_load_dwordx4 v[232:235], v[174:175], off offset:16
	global_load_dwordx4 v[236:239], v[174:175], off offset:512
	global_load_dwordx4 v[240:243], v[174:175], off offset:528
	v_lshl_add_u64 v[174:175], v[174:175], 0, s[92:93]
	global_load_dwordx4 v[158:161], v[174:175], off
	global_load_dwordx4 v[162:165], v[174:175], off offset:16
	global_load_dwordx4 v[166:169], v[174:175], off offset:512
	global_load_dwordx4 v[170:173], v[174:175], off offset:528
	v_lshl_add_u64 v[174:175], v[174:175], 0, s[92:93]
	v_lshlrev_b64 v[178:179], 11, v[150:151]
	v_lshl_add_u64 v[178:179], s[14:15], 0, v[178:179]
	v_lshl_add_u64 v[178:179], v[148:149], 1, v[178:179]
	v_lshl_add_u64 v[180:181], v[150:151], 2, s[16:17]
	s_waitcnt vmcnt(8)
	v_pk_add_f32 v[124:125], v[124:125], v[206:207]
	v_pk_add_f32 v[126:127], v[126:127], v[208:209]
	v_pk_add_f32 v[120:121], v[120:121], v[210:211]
	v_pk_add_f32 v[122:123], v[122:123], v[212:213]
	v_pk_add_f32 v[116:117], v[116:117], v[214:215]
	v_pk_add_f32 v[118:119], v[118:119], v[216:217]
	v_pk_add_f32 v[112:113], v[112:113], v[218:219]
	v_pk_add_f32 v[114:115], v[114:115], v[220:221]
	global_load_dwordx4 v[206:209], v[174:175], off
	global_load_dwordx4 v[210:213], v[174:175], off offset:16
	global_load_dwordx4 v[214:217], v[174:175], off offset:512
	global_load_dwordx4 v[218:221], v[174:175], off offset:528
	v_lshl_add_u64 v[174:175], v[174:175], 0, s[94:95]
	v_mul_f32_e32 v182, v124, v124
	v_mul_f32_e32 v183, v125, v125
	v_fmac_f32_e32 v182, v126, v126
	v_fmac_f32_e32 v183, v127, v127
	v_fmac_f32_e32 v182, v120, v120
	v_fmac_f32_e32 v183, v121, v121
	v_fmac_f32_e32 v182, v122, v122
	v_fmac_f32_e32 v183, v123, v123
	v_fmac_f32_e32 v182, v116, v116
	v_fmac_f32_e32 v183, v117, v117
	v_fmac_f32_e32 v182, v118, v118
	v_fmac_f32_e32 v183, v119, v119
	v_fmac_f32_e32 v182, v112, v112
	v_fmac_f32_e32 v183, v113, v113
	v_fmac_f32_e32 v182, v114, v114
	v_fmac_f32_e32 v183, v115, v115
	v_add_f32_e32 v182, v182, v183
	ds_bpermute_b32 v184, v205, v182
	v_pk_mul_f32 v[124:125], v[124:125], v[186:187]
	v_pk_mul_f32 v[126:127], v[126:127], v[188:189]
	v_pk_mul_f32 v[120:121], v[120:121], v[190:191]
	v_pk_mul_f32 v[122:123], v[122:123], v[192:193]
	v_pk_mul_f32 v[116:117], v[116:117], v[194:195]
	v_pk_mul_f32 v[118:119], v[118:119], v[196:197]
	v_pk_mul_f32 v[112:113], v[112:113], v[198:199]
	v_pk_mul_f32 v[114:115], v[114:115], v[200:201]
	v_cvt_pk_bf16_f32 v124, v124, v125
	v_cvt_pk_bf16_f32 v125, v126, v127
	v_cvt_pk_bf16_f32 v126, v120, v121
	v_cvt_pk_bf16_f32 v127, v122, v123
	v_cvt_pk_bf16_f32 v116, v116, v117
	v_cvt_pk_bf16_f32 v117, v118, v119
	v_cvt_pk_bf16_f32 v118, v112, v113
	v_cvt_pk_bf16_f32 v119, v114, v115
	global_store_dwordx4 v[178:179], v[124:127], off
	global_store_dwordx4 v[178:179], v[116:119], off offset:256
	v_lshl_add_u64 v[178:179], v[178:179], 0, s[96:97]
	s_waitcnt lgkmcnt(0)
	v_add_f32_e32 v182, v182, v184
	ds_bpermute_b32 v184, v225, v182
	s_waitcnt lgkmcnt(0)
	v_add_f32_e32 v182, v182, v184
	s_and_saveexec_b64 s[34:35], s[0:1]
	global_atomic_add_f32 v[180:181], v182, off
	s_or_b64 exec, exec, s[34:35]
	s_waitcnt vmcnt(10)
	v_pk_add_f32 v[108:109], v[108:109], v[228:229]
	v_pk_add_f32 v[110:111], v[110:111], v[230:231]
	v_pk_add_f32 v[104:105], v[104:105], v[232:233]
	v_pk_add_f32 v[106:107], v[106:107], v[234:235]
	v_pk_add_f32 v[100:101], v[100:101], v[236:237]
	v_pk_add_f32 v[102:103], v[102:103], v[238:239]
	v_pk_add_f32 v[96:97], v[96:97], v[240:241]
	v_pk_add_f32 v[98:99], v[98:99], v[242:243]
	global_load_dwordx4 v[228:231], v[174:175], off
	global_load_dwordx4 v[232:235], v[174:175], off offset:16
	global_load_dwordx4 v[236:239], v[174:175], off offset:512
	global_load_dwordx4 v[240:243], v[174:175], off offset:528
	v_lshl_add_u64 v[174:175], v[174:175], 0, s[92:93]
	v_mul_f32_e32 v182, v108, v108
	v_mul_f32_e32 v183, v109, v109
	v_fmac_f32_e32 v182, v110, v110
	v_fmac_f32_e32 v183, v111, v111
	v_fmac_f32_e32 v182, v104, v104
	v_fmac_f32_e32 v183, v105, v105
	v_fmac_f32_e32 v182, v106, v106
	v_fmac_f32_e32 v183, v107, v107
	v_fmac_f32_e32 v182, v100, v100
	v_fmac_f32_e32 v183, v101, v101
	v_fmac_f32_e32 v182, v102, v102
	v_fmac_f32_e32 v183, v103, v103
	v_fmac_f32_e32 v182, v96, v96
	v_fmac_f32_e32 v183, v97, v97
	v_fmac_f32_e32 v182, v98, v98
	v_fmac_f32_e32 v183, v99, v99
	v_add_f32_e32 v182, v182, v183
	ds_bpermute_b32 v184, v205, v182
	v_pk_mul_f32 v[108:109], v[108:109], v[186:187]
	v_pk_mul_f32 v[110:111], v[110:111], v[188:189]
	v_pk_mul_f32 v[104:105], v[104:105], v[190:191]
	v_pk_mul_f32 v[106:107], v[106:107], v[192:193]
	v_pk_mul_f32 v[100:101], v[100:101], v[194:195]
	v_pk_mul_f32 v[102:103], v[102:103], v[196:197]
	v_pk_mul_f32 v[96:97], v[96:97], v[198:199]
	v_pk_mul_f32 v[98:99], v[98:99], v[200:201]
	v_cvt_pk_bf16_f32 v108, v108, v109
	v_cvt_pk_bf16_f32 v109, v110, v111
	v_cvt_pk_bf16_f32 v110, v104, v105
	v_cvt_pk_bf16_f32 v111, v106, v107
	v_cvt_pk_bf16_f32 v100, v100, v101
	v_cvt_pk_bf16_f32 v101, v102, v103
	v_cvt_pk_bf16_f32 v102, v96, v97
	v_cvt_pk_bf16_f32 v103, v98, v99
	global_store_dwordx4 v[178:179], v[108:111], off
	global_store_dwordx4 v[178:179], v[100:103], off offset:256
	v_lshl_add_u64 v[178:179], v[178:179], 0, s[96:97]
	s_waitcnt lgkmcnt(0)
; __device__ __forceinline__ u32x4 pack8(f32x4 a, f32x4 b) { u32x4 w; w.x = pk2(a[0], a[1]); w.y = pk2(a[2], a[3]); w.z = pk2(b[0], b[1]); w.w = pk2(b[2], b[3]); return w; }
;     __device__ __forceinline__ void operator()(const f32x4 (&acc)[2][2][4][2], const Unit& u, int wr, int wc, int fr, int fq) const {
;     ...
;                 const int r = u.pm * 256 + ai * 128 + wr * 64 + m * 16 + fr;
;                 const float* x = r < MP ? xp + (size_t)r * 1024 : xs + (size_t)(r - MP) * 1024;
;                 float ss = 0.f;
; #pragma unroll
;                 for (int bj = 0; bj < 2; ++bj) {
;                     const int c = u.pn * 256 + 128 * bj + 32 * wc + 8 * fq;
;                     const f32x4 r0 = *(const f32x4*)(x + c), r1 = *(const f32x4*)(x + c + 4);
;                     const f32x4 y0 = r0 + acc[ai][bj][m][0], y1 = r1 + acc[ai][bj][m][1];
;                     const f32x4 g0 = *(const f32x4*)(gain + c), g1 = *(const f32x4*)(gain + c + 4);
;                     *(u32x4*)(h2 + (size_t)r * 1024 + c) = pack8(y0 * g0, y1 * g1);
;                     ss += (y0[0] * y0[0] + y0[1] * y0[1]) + (y0[2] * y0[2] + y0[3] * y0[3]) + (y1[0] * y1[0] + y1[1] * y1[1]) + (y1[2] * y1[2] + y1[3] * y1[3]);
;                 }
;                 ss += __shfl_xor(ss, 16); ss += __shfl_xor(ss, 32);
;                 if (fq == 0) atomicAdd(rowsq + r, ss);
	v_add_f32_e32 v182, v182, v184
	ds_bpermute_b32 v184, v225, v182
	s_waitcnt lgkmcnt(0)
	v_add_f32_e32 v182, v182, v184
	s_and_saveexec_b64 s[34:35], s[0:1]
	global_atomic_add_f32 v[180:181], v182, off offset:64
	s_or_b64 exec, exec, s[34:35]
	s_waitcnt vmcnt(12)
	v_pk_add_f32 v[92:93], v[92:93], v[158:159]
	v_pk_add_f32 v[94:95], v[94:95], v[160:161]
	v_pk_add_f32 v[88:89], v[88:89], v[162:163]
	v_pk_add_f32 v[90:91], v[90:91], v[164:165]
	v_pk_add_f32 v[84:85], v[84:85], v[166:167]
	v_pk_add_f32 v[86:87], v[86:87], v[168:169]
	v_pk_add_f32 v[80:81], v[80:81], v[170:171]
	v_pk_add_f32 v[82:83], v[82:83], v[172:173]
	global_load_dwordx4 v[158:161], v[174:175], off
	global_load_dwordx4 v[162:165], v[174:175], off offset:16
	global_load_dwordx4 v[166:169], v[174:175], off offset:512
	global_load_dwordx4 v[170:173], v[174:175], off offset:528
	v_lshl_add_u64 v[174:175], v[174:175], 0, s[92:93]
	v_mul_f32_e32 v182, v92, v92
	v_mul_f32_e32 v183, v93, v93
	v_fmac_f32_e32 v182, v94, v94
	v_fmac_f32_e32 v183, v95, v95
	v_fmac_f32_e32 v182, v88, v88
	v_fmac_f32_e32 v183, v89, v89
	v_fmac_f32_e32 v182, v90, v90
	v_fmac_f32_e32 v183, v91, v91
	v_fmac_f32_e32 v182, v84, v84
	v_fmac_f32_e32 v183, v85, v85
	v_fmac_f32_e32 v182, v86, v86
	v_fmac_f32_e32 v183, v87, v87
	v_fmac_f32_e32 v182, v80, v80
	v_fmac_f32_e32 v183, v81, v81
	v_fmac_f32_e32 v182, v82, v82
	v_fmac_f32_e32 v183, v83, v83
	v_add_f32_e32 v182, v182, v183
	ds_bpermute_b32 v184, v205, v182
	v_pk_mul_f32 v[92:93], v[92:93], v[186:187]
	v_pk_mul_f32 v[94:95], v[94:95], v[188:189]
	v_pk_mul_f32 v[88:89], v[88:89], v[190:191]
	v_pk_mul_f32 v[90:91], v[90:91], v[192:193]
	v_pk_mul_f32 v[84:85], v[84:85], v[194:195]
	v_pk_mul_f32 v[86:87], v[86:87], v[196:197]
	v_pk_mul_f32 v[80:81], v[80:81], v[198:199]
	v_pk_mul_f32 v[82:83], v[82:83], v[200:201]
	v_cvt_pk_bf16_f32 v92, v92, v93
	v_cvt_pk_bf16_f32 v93, v94, v95
	v_cvt_pk_bf16_f32 v94, v88, v89
	v_cvt_pk_bf16_f32 v95, v90, v91
	v_cvt_pk_bf16_f32 v84, v84, v85
	v_cvt_pk_bf16_f32 v85, v86, v87
	v_cvt_pk_bf16_f32 v86, v80, v81
	v_cvt_pk_bf16_f32 v87, v82, v83
	global_store_dwordx4 v[178:179], v[92:95], off
	global_store_dwordx4 v[178:179], v[84:87], off offset:256
	v_lshl_add_u64 v[178:179], v[178:179], 0, s[96:97]
	s_waitcnt lgkmcnt(0)
	v_add_f32_e32 v182, v182, v184
	ds_bpermute_b32 v184, v225, v182
	s_waitcnt lgkmcnt(0)
	v_add_f32_e32 v182, v182, v184
	s_and_saveexec_b64 s[34:35], s[0:1]
	global_atomic_add_f32 v[180:181], v182, off offset:128
	s_or_b64 exec, exec, s[34:35]
	s_waitcnt vmcnt(12)
	v_pk_add_f32 v[76:77], v[76:77], v[206:207]
	v_pk_add_f32 v[78:79], v[78:79], v[208:209]
	v_pk_add_f32 v[72:73], v[72:73], v[210:211]
	v_pk_add_f32 v[74:75], v[74:75], v[212:213]
	v_pk_add_f32 v[68:69], v[68:69], v[214:215]
	v_pk_add_f32 v[70:71], v[70:71], v[216:217]
	v_pk_add_f32 v[64:65], v[64:65], v[218:219]
	v_pk_add_f32 v[66:67], v[66:67], v[220:221]
	global_load_dwordx4 v[206:209], v[174:175], off
	global_load_dwordx4 v[210:213], v[174:175], off offset:16
	global_load_dwordx4 v[214:217], v[174:175], off offset:512
	global_load_dwordx4 v[218:221], v[174:175], off offset:528
	v_lshl_add_u64 v[174:175], v[174:175], 0, s[92:93]
	v_mul_f32_e32 v182, v76, v76
	v_mul_f32_e32 v183, v77, v77
	v_fmac_f32_e32 v182, v78, v78
	v_fmac_f32_e32 v183, v79, v79
	v_fmac_f32_e32 v182, v72, v72
	v_fmac_f32_e32 v183, v73, v73
	v_fmac_f32_e32 v182, v74, v74
	v_fmac_f32_e32 v183, v75, v75
	v_fmac_f32_e32 v182, v68, v68
	v_fmac_f32_e32 v183, v69, v69
	v_fmac_f32_e32 v182, v70, v70
	v_fmac_f32_e32 v183, v71, v71
	v_fmac_f32_e32 v182, v64, v64
	v_fmac_f32_e32 v183, v65, v65
	v_fmac_f32_e32 v182, v66, v66
	v_fmac_f32_e32 v183, v67, v67
	v_add_f32_e32 v182, v182, v183
	ds_bpermute_b32 v184, v205, v182
	v_pk_mul_f32 v[76:77], v[76:77], v[186:187]
	v_pk_mul_f32 v[78:79], v[78:79], v[188:189]
	v_pk_mul_f32 v[72:73], v[72:73], v[190:191]
	v_pk_mul_f32 v[74:75], v[74:75], v[192:193]
	v_pk_mul_f32 v[68:69], v[68:69], v[194:195]
	v_pk_mul_f32 v[70:71], v[70:71], v[196:197]
	v_pk_mul_f32 v[64:65], v[64:65], v[198:199]
	v_pk_mul_f32 v[66:67], v[66:67], v[200:201]
	v_cvt_pk_bf16_f32 v76, v76, v77
	v_cvt_pk_bf16_f32 v77, v78, v79
	v_cvt_pk_bf16_f32 v78, v72, v73
	v_cvt_pk_bf16_f32 v79, v74, v75
	v_cvt_pk_bf16_f32 v68, v68, v69
	v_cvt_pk_bf16_f32 v69, v70, v71
	v_cvt_pk_bf16_f32 v70, v64, v65
	v_cvt_pk_bf16_f32 v71, v66, v67
	global_store_dwordx4 v[178:179], v[76:79], off
	global_store_dwordx4 v[178:179], v[68:71], off offset:256
	v_lshl_add_u64 v[178:179], v[178:179], 0, s[98:99]
	s_waitcnt lgkmcnt(0)
	v_add_f32_e32 v182, v182, v184
	ds_bpermute_b32 v184, v225, v182
	s_waitcnt lgkmcnt(0)
	v_add_f32_e32 v182, v182, v184
	s_and_saveexec_b64 s[34:35], s[0:1]
	global_atomic_add_f32 v[180:181], v182, off offset:192
	s_or_b64 exec, exec, s[34:35]
	s_waitcnt vmcnt(12)
; __device__ __forceinline__ u32x4 pack8(f32x4 a, f32x4 b) { u32x4 w; w.x = pk2(a[0], a[1]); w.y = pk2(a[2], a[3]); w.z = pk2(b[0], b[1]); w.w = pk2(b[2], b[3]); return w; }
;     __device__ __forceinline__ void operator()(const f32x4 (&acc)[2][2][4][2], const Unit& u, int wr, int wc, int fr, int fq) const {
;     ...
;                 const int r = u.pm * 256 + ai * 128 + wr * 64 + m * 16 + fr;
;                 const float* x = r < MP ? xp + (size_t)r * 1024 : xs + (size_t)(r - MP) * 1024;
;                 float ss = 0.f;
; #pragma unroll
;                 for (int bj = 0; bj < 2; ++bj) {
;                     const int c = u.pn * 256 + 128 * bj + 32 * wc + 8 * fq;
;                     const f32x4 r0 = *(const f32x4*)(x + c), r1 = *(const f32x4*)(x + c + 4);
;                     const f32x4 y0 = r0 + acc[ai][bj][m][0], y1 = r1 + acc[ai][bj][m][1];
;                     const f32x4 g0 = *(const f32x4*)(gain + c), g1 = *(const f32x4*)(gain + c + 4);
;                     *(u32x4*)(h2 + (size_t)r * 1024 + c) = pack8(y0 * g0, y1 * g1);
;                     ss += (y0[0] * y0[0] + y0[1] * y0[1]) + (y0[2] * y0[2] + y0[3] * y0[3]) + (y1[0] * y1[0] + y1[1] * y1[1]) + (y1[2] * y1[2] + y1[3] * y1[3]);
;                 }
;                 ss += __shfl_xor(ss, 16); ss += __shfl_xor(ss, 32);
;                 if (fq == 0) atomicAdd(rowsq + r, ss);
	v_pk_add_f32 v[60:61], v[60:61], v[228:229]
	v_pk_add_f32 v[62:63], v[62:63], v[230:231]
	v_pk_add_f32 v[56:57], v[56:57], v[232:233]
	v_pk_add_f32 v[58:59], v[58:59], v[234:235]
	v_pk_add_f32 v[52:53], v[52:53], v[236:237]
	v_pk_add_f32 v[54:55], v[54:55], v[238:239]
	v_pk_add_f32 v[48:49], v[48:49], v[240:241]
	v_pk_add_f32 v[50:51], v[50:51], v[242:243]
	global_load_dwordx4 v[228:231], v[174:175], off
	global_load_dwordx4 v[232:235], v[174:175], off offset:16
	global_load_dwordx4 v[236:239], v[174:175], off offset:512
	global_load_dwordx4 v[240:243], v[174:175], off offset:528
	v_mul_f32_e32 v182, v60, v60
	v_mul_f32_e32 v183, v61, v61
	v_fmac_f32_e32 v182, v62, v62
	v_fmac_f32_e32 v183, v63, v63
	v_fmac_f32_e32 v182, v56, v56
	v_fmac_f32_e32 v183, v57, v57
	v_fmac_f32_e32 v182, v58, v58
	v_fmac_f32_e32 v183, v59, v59
	v_fmac_f32_e32 v182, v52, v52
	v_fmac_f32_e32 v183, v53, v53
	v_fmac_f32_e32 v182, v54, v54
	v_fmac_f32_e32 v183, v55, v55
	v_fmac_f32_e32 v182, v48, v48
	v_fmac_f32_e32 v183, v49, v49
	v_fmac_f32_e32 v182, v50, v50
	v_fmac_f32_e32 v183, v51, v51
	v_add_f32_e32 v182, v182, v183
	ds_bpermute_b32 v184, v205, v182
	v_pk_mul_f32 v[60:61], v[60:61], v[186:187]
	v_pk_mul_f32 v[62:63], v[62:63], v[188:189]
	v_pk_mul_f32 v[56:57], v[56:57], v[190:191]
	v_pk_mul_f32 v[58:59], v[58:59], v[192:193]
	v_pk_mul_f32 v[52:53], v[52:53], v[194:195]
	v_pk_mul_f32 v[54:55], v[54:55], v[196:197]
	v_pk_mul_f32 v[48:49], v[48:49], v[198:199]
	v_pk_mul_f32 v[50:51], v[50:51], v[200:201]
	v_cvt_pk_bf16_f32 v60, v60, v61
	v_cvt_pk_bf16_f32 v61, v62, v63
	v_cvt_pk_bf16_f32 v62, v56, v57
	v_cvt_pk_bf16_f32 v63, v58, v59
	v_cvt_pk_bf16_f32 v52, v52, v53
	v_cvt_pk_bf16_f32 v53, v54, v55
	v_cvt_pk_bf16_f32 v54, v48, v49
	v_cvt_pk_bf16_f32 v55, v50, v51
	global_store_dwordx4 v[178:179], v[60:63], off
	global_store_dwordx4 v[178:179], v[52:55], off offset:256
	v_lshl_add_u64 v[178:179], v[178:179], 0, s[96:97]
	s_waitcnt lgkmcnt(0)
	v_add_f32_e32 v182, v182, v184
	ds_bpermute_b32 v184, v225, v182
	s_waitcnt lgkmcnt(0)
	v_add_f32_e32 v182, v182, v184
	s_and_saveexec_b64 s[34:35], s[0:1]
	global_atomic_add_f32 v[180:181], v182, off offset:512
	s_or_b64 exec, exec, s[34:35]
	s_waitcnt vmcnt(12)
	v_pk_add_f32 v[44:45], v[44:45], v[158:159]
	v_pk_add_f32 v[46:47], v[46:47], v[160:161]
	v_pk_add_f32 v[40:41], v[40:41], v[162:163]
	v_pk_add_f32 v[42:43], v[42:43], v[164:165]
	v_pk_add_f32 v[36:37], v[36:37], v[166:167]
	v_pk_add_f32 v[38:39], v[38:39], v[168:169]
	v_pk_add_f32 v[32:33], v[32:33], v[170:171]
	v_pk_add_f32 v[34:35], v[34:35], v[172:173]
	v_mul_f32_e32 v182, v44, v44
	v_mul_f32_e32 v183, v45, v45
	v_fmac_f32_e32 v182, v46, v46
	v_fmac_f32_e32 v183, v47, v47
	v_fmac_f32_e32 v182, v40, v40
	v_fmac_f32_e32 v183, v41, v41
	v_fmac_f32_e32 v182, v42, v42
	v_fmac_f32_e32 v183, v43, v43
	v_fmac_f32_e32 v182, v36, v36
	v_fmac_f32_e32 v183, v37, v37
	v_fmac_f32_e32 v182, v38, v38
	v_fmac_f32_e32 v183, v39, v39
	v_fmac_f32_e32 v182, v32, v32
	v_fmac_f32_e32 v183, v33, v33
	v_fmac_f32_e32 v182, v34, v34
	v_fmac_f32_e32 v183, v35, v35
	v_add_f32_e32 v182, v182, v183
	ds_bpermute_b32 v184, v205, v182
	v_pk_mul_f32 v[44:45], v[44:45], v[186:187]
	v_pk_mul_f32 v[46:47], v[46:47], v[188:189]
	v_pk_mul_f32 v[40:41], v[40:41], v[190:191]
	v_pk_mul_f32 v[42:43], v[42:43], v[192:193]
	v_pk_mul_f32 v[36:37], v[36:37], v[194:195]
	v_pk_mul_f32 v[38:39], v[38:39], v[196:197]
	v_pk_mul_f32 v[32:33], v[32:33], v[198:199]
	v_pk_mul_f32 v[34:35], v[34:35], v[200:201]
	v_cvt_pk_bf16_f32 v44, v44, v45
	v_cvt_pk_bf16_f32 v45, v46, v47
	v_cvt_pk_bf16_f32 v46, v40, v41
	v_cvt_pk_bf16_f32 v47, v42, v43
	v_cvt_pk_bf16_f32 v36, v36, v37
	v_cvt_pk_bf16_f32 v37, v38, v39
	v_cvt_pk_bf16_f32 v38, v32, v33
	v_cvt_pk_bf16_f32 v39, v34, v35
	global_store_dwordx4 v[178:179], v[44:47], off
	global_store_dwordx4 v[178:179], v[36:39], off offset:256
	v_lshl_add_u64 v[178:179], v[178:179], 0, s[96:97]
	s_waitcnt lgkmcnt(0)
	v_add_f32_e32 v182, v182, v184
	ds_bpermute_b32 v184, v225, v182
	s_waitcnt lgkmcnt(0)
; __device__ __forceinline__ u32x4 pack8(f32x4 a, f32x4 b) { u32x4 w; w.x = pk2(a[0], a[1]); w.y = pk2(a[2], a[3]); w.z = pk2(b[0], b[1]); w.w = pk2(b[2], b[3]); return w; }
;     __device__ __forceinline__ void operator()(const f32x4 (&acc)[2][2][4][2], const Unit& u, int wr, int wc, int fr, int fq) const {
;     ...
;                 const int r = u.pm * 256 + ai * 128 + wr * 64 + m * 16 + fr;
;                 const float* x = r < MP ? xp + (size_t)r * 1024 : xs + (size_t)(r - MP) * 1024;
;                 float ss = 0.f;
; #pragma unroll
;                 for (int bj = 0; bj < 2; ++bj) {
;                     const int c = u.pn * 256 + 128 * bj + 32 * wc + 8 * fq;
;                     const f32x4 r0 = *(const f32x4*)(x + c), r1 = *(const f32x4*)(x + c + 4);
;                     const f32x4 y0 = r0 + acc[ai][bj][m][0], y1 = r1 + acc[ai][bj][m][1];
;                     const f32x4 g0 = *(const f32x4*)(gain + c), g1 = *(const f32x4*)(gain + c + 4);
;                     *(u32x4*)(h2 + (size_t)r * 1024 + c) = pack8(y0 * g0, y1 * g1);
;                     ss += (y0[0] * y0[0] + y0[1] * y0[1]) + (y0[2] * y0[2] + y0[3] * y0[3]) + (y1[0] * y1[0] + y1[1] * y1[1]) + (y1[2] * y1[2] + y1[3] * y1[3]);
;                 }
;                 ss += __shfl_xor(ss, 16); ss += __shfl_xor(ss, 32);
;                 if (fq == 0) atomicAdd(rowsq + r, ss);
	v_add_f32_e32 v182, v182, v184
	s_and_saveexec_b64 s[34:35], s[0:1]
	global_atomic_add_f32 v[180:181], v182, off offset:576
	s_or_b64 exec, exec, s[34:35]
	s_waitcnt vmcnt(10)
	v_pk_add_f32 v[28:29], v[28:29], v[206:207]
	v_pk_add_f32 v[30:31], v[30:31], v[208:209]
	v_pk_add_f32 v[24:25], v[24:25], v[210:211]
	v_pk_add_f32 v[26:27], v[26:27], v[212:213]
	v_pk_add_f32 v[20:21], v[20:21], v[214:215]
	v_pk_add_f32 v[22:23], v[22:23], v[216:217]
	v_pk_add_f32 v[16:17], v[16:17], v[218:219]
	v_pk_add_f32 v[18:19], v[18:19], v[220:221]
	v_mul_f32_e32 v182, v28, v28
	v_mul_f32_e32 v183, v29, v29
	v_fmac_f32_e32 v182, v30, v30
	v_fmac_f32_e32 v183, v31, v31
	v_fmac_f32_e32 v182, v24, v24
	v_fmac_f32_e32 v183, v25, v25
	v_fmac_f32_e32 v182, v26, v26
	v_fmac_f32_e32 v183, v27, v27
	v_fmac_f32_e32 v182, v20, v20
	v_fmac_f32_e32 v183, v21, v21
	v_fmac_f32_e32 v182, v22, v22
	v_fmac_f32_e32 v183, v23, v23
	v_fmac_f32_e32 v182, v16, v16
	v_fmac_f32_e32 v183, v17, v17
	v_fmac_f32_e32 v182, v18, v18
	v_fmac_f32_e32 v183, v19, v19
	v_add_f32_e32 v182, v182, v183
	ds_bpermute_b32 v184, v205, v182
	v_pk_mul_f32 v[28:29], v[28:29], v[186:187]
	v_pk_mul_f32 v[30:31], v[30:31], v[188:189]
	v_pk_mul_f32 v[24:25], v[24:25], v[190:191]
	v_pk_mul_f32 v[26:27], v[26:27], v[192:193]
	v_pk_mul_f32 v[20:21], v[20:21], v[194:195]
	v_pk_mul_f32 v[22:23], v[22:23], v[196:197]
	v_pk_mul_f32 v[16:17], v[16:17], v[198:199]
	v_pk_mul_f32 v[18:19], v[18:19], v[200:201]
	v_cvt_pk_bf16_f32 v28, v28, v29
	v_cvt_pk_bf16_f32 v29, v30, v31
	v_cvt_pk_bf16_f32 v30, v24, v25
	v_cvt_pk_bf16_f32 v31, v26, v27
	v_cvt_pk_bf16_f32 v20, v20, v21
	v_cvt_pk_bf16_f32 v21, v22, v23
	v_cvt_pk_bf16_f32 v22, v16, v17
	v_cvt_pk_bf16_f32 v23, v18, v19
	global_store_dwordx4 v[178:179], v[28:31], off
	global_store_dwordx4 v[178:179], v[20:23], off offset:256
	v_lshl_add_u64 v[178:179], v[178:179], 0, s[96:97]
	s_waitcnt lgkmcnt(0)
	v_add_f32_e32 v182, v182, v184
	ds_bpermute_b32 v184, v225, v182
	s_waitcnt lgkmcnt(0)
	v_add_f32_e32 v182, v182, v184
	s_and_saveexec_b64 s[34:35], s[0:1]
	global_atomic_add_f32 v[180:181], v182, off offset:640
	s_or_b64 exec, exec, s[34:35]
	s_waitcnt vmcnt(6)
	v_pk_add_f32 v[12:13], v[12:13], v[228:229]
	v_pk_add_f32 v[14:15], v[14:15], v[230:231]
	v_pk_add_f32 v[8:9], v[8:9], v[232:233]
	v_pk_add_f32 v[10:11], v[10:11], v[234:235]
	v_pk_add_f32 v[4:5], v[4:5], v[236:237]
	v_pk_add_f32 v[6:7], v[6:7], v[238:239]
	v_pk_add_f32 v[0:1], v[0:1], v[240:241]
	v_pk_add_f32 v[2:3], v[2:3], v[242:243]
	v_mul_f32_e32 v182, v12, v12
	v_mul_f32_e32 v183, v13, v13
	v_fmac_f32_e32 v182, v14, v14
	v_fmac_f32_e32 v183, v15, v15
	v_fmac_f32_e32 v182, v8, v8
	v_fmac_f32_e32 v183, v9, v9
	v_fmac_f32_e32 v182, v10, v10
	v_fmac_f32_e32 v183, v11, v11
	v_fmac_f32_e32 v182, v4, v4
	v_fmac_f32_e32 v183, v5, v5
	v_fmac_f32_e32 v182, v6, v6
	v_fmac_f32_e32 v183, v7, v7
	v_fmac_f32_e32 v182, v0, v0
	v_fmac_f32_e32 v183, v1, v1
	v_fmac_f32_e32 v182, v2, v2
	v_fmac_f32_e32 v183, v3, v3
	v_add_f32_e32 v182, v182, v183
	ds_bpermute_b32 v184, v205, v182
	v_pk_mul_f32 v[12:13], v[12:13], v[186:187]
	v_pk_mul_f32 v[14:15], v[14:15], v[188:189]
	v_pk_mul_f32 v[8:9], v[8:9], v[190:191]
	v_pk_mul_f32 v[10:11], v[10:11], v[192:193]
	v_pk_mul_f32 v[4:5], v[4:5], v[194:195]
	v_pk_mul_f32 v[6:7], v[6:7], v[196:197]
	v_pk_mul_f32 v[0:1], v[0:1], v[198:199]
	v_pk_mul_f32 v[2:3], v[2:3], v[200:201]
	v_cvt_pk_bf16_f32 v12, v12, v13
	v_cvt_pk_bf16_f32 v13, v14, v15
	v_cvt_pk_bf16_f32 v14, v8, v9
	v_cvt_pk_bf16_f32 v15, v10, v11
	v_cvt_pk_bf16_f32 v4, v4, v5
	v_cvt_pk_bf16_f32 v5, v6, v7
	v_cvt_pk_bf16_f32 v6, v0, v1
	v_cvt_pk_bf16_f32 v7, v2, v3
	global_store_dwordx4 v[178:179], v[12:15], off
	global_store_dwordx4 v[178:179], v[4:7], off offset:256
	s_waitcnt lgkmcnt(0)
	v_add_f32_e32 v182, v182, v184
	ds_bpermute_b32 v184, v225, v182
	s_waitcnt lgkmcnt(0)
	v_add_f32_e32 v182, v182, v184
	s_and_saveexec_b64 s[34:35], s[0:1]
	global_atomic_add_f32 v[180:181], v182, off offset:704
	s_or_b64 exec, exec, s[34:35]
	s_andn2_b64 vcc, exec, s[4:5]
	s_mov_b64 s[4:5], -1
	s_cbranch_vccnz .LBB0_926
	s_andn2_b64 vcc, exec, s[12:13]
	s_cbranch_vccnz .LBB0_925
	s_barrier
	s_branch .LBB0_925

;     __device__ __forceinline__ const float* in(int k) const { return (const float*)(const GAS float*)ld(k); }
;     __device__ __forceinline__ unsigned char* ws() const { return (unsigned char*)(GAS unsigned char*)ld(26); }
; #define PH(k) if ((MK_MASK >> (k)) & 1)
; __global__ void __launch_bounds__(512, 2) fwd_kernel(Params KP) {
;     ...
;     PH(6) {
;         unsigned char* ws = P.ws();
;         pg8::Gemm g{(const bf16_t*)(ws + WS_ACT), (const bf16_t*)(ws + WS_WOUT), MT, 1024, 1024}; pg8::StaticOrder S; S.init(MT, 1024, G, c);
;         EpiOut E{P.in(0), P.in(1), (bf16_t*)(ws + WS_H2), P.in(19), (float*)(ws + WS_RSQ)};
;         pg8::gemm_phase<EpiOut, pg8::StaticOrder, true, true>(lds, g, S, E, phase_tid(wid_s));
;     }
	.amdhsa_kernel _ZN2mk10fwd_kernelENS_6ParamsE
		.amdhsa_group_segment_fixed_size 0
		.amdhsa_private_segment_fixed_size 0
		.amdhsa_kernarg_size 472
		.amdhsa_user_sgpr_count 2
		.amdhsa_user_sgpr_dispatch_ptr 0
		.amdhsa_user_sgpr_queue_ptr 0
		.amdhsa_user_sgpr_kernarg_segment_ptr 1
		.amdhsa_user_sgpr_dispatch_id 0
		.amdhsa_user_sgpr_kernarg_preload_length 0
		.amdhsa_user_sgpr_kernarg_preload_offset 0
		.amdhsa_user_sgpr_private_segment_size 0
		.amdhsa_uses_dynamic_stack 0
		.amdhsa_enable_private_segment 0
		.amdhsa_system_sgpr_workgroup_id_x 1
		.amdhsa_system_sgpr_workgroup_id_y 0
		.amdhsa_system_sgpr_workgroup_id_z 0
		.amdhsa_system_sgpr_workgroup_info 0
		.amdhsa_system_vgpr_workitem_id 2
		.amdhsa_next_free_vgpr 256
		.amdhsa_next_free_sgpr 100
		.amdhsa_accum_offset 256
		.amdhsa_reserve_vcc 1
		.amdhsa_float_round_mode_32 0
		.amdhsa_float_round_mode_16_64 0
		.amdhsa_float_denorm_mode_32 3
		.amdhsa_float_denorm_mode_16_64 3
		.amdhsa_dx10_clamp 1
		.amdhsa_ieee_mode 1
		.amdhsa_fp16_overflow 0
		.amdhsa_tg_split 0
		.amdhsa_exception_fp_ieee_invalid_op 0
		.amdhsa_exception_fp_denorm_src 0
		.amdhsa_exception_fp_ieee_div_zero 0
		.amdhsa_exception_fp_ieee_overflow 0
		.amdhsa_exception_fp_ieee_underflow 0
		.amdhsa_exception_fp_ieee_inexact 0
		.amdhsa_exception_int_div_zero 0
	.end_amdhsa_kernel

;     __device__ __forceinline__ const float* in(int k) const { return (const float*)(const GAS float*)ld(k); }
;     __device__ __forceinline__ unsigned char* ws() const { return (unsigned char*)(GAS unsigned char*)ld(26); }
; #define PH(k) if ((MK_MASK >> (k)) & 1)
; __global__ void __launch_bounds__(512, 2) fwd_kernel(Params KP) {
;     ...
;     PH(6) {
;         unsigned char* ws = P.ws();
;         pg8::Gemm g{(const bf16_t*)(ws + WS_ACT), (const bf16_t*)(ws + WS_WOUT), MT, 1024, 1024}; pg8::StaticOrder S; S.init(MT, 1024, G, c);
;         EpiOut E{P.in(0), P.in(1), (bf16_t*)(ws + WS_H2), P.in(19), (float*)(ws + WS_RSQ)};
;         pg8::gemm_phase<EpiOut, pg8::StaticOrder, true, true>(lds, g, S, E, phase_tid(wid_s));
;     }
amdhsa.kernels:
  - .agpr_count:     0
    .args:
      - .offset:         0
        .size:           216
        .value_kind:     by_value
      - .offset:         216
        .size:           4
        .value_kind:     hidden_block_count_x
      - .offset:         220
        .size:           4
        .value_kind:     hidden_block_count_y
      - .offset:         224
        .size:           4
        .value_kind:     hidden_block_count_z
      - .offset:         228
        .size:           2
        .value_kind:     hidden_group_size_x
      - .offset:         230
        .size:           2
        .value_kind:     hidden_group_size_y
      - .offset:         232
        .size:           2
        .value_kind:     hidden_group_size_z
      - .offset:         234
        .size:           2
        .value_kind:     hidden_remainder_x
      - .offset:         236
        .size:           2
        .value_kind:     hidden_remainder_y
      - .offset:         238
        .size:           2
        .value_kind:     hidden_remainder_z
      - .offset:         256
        .size:           8
        .value_kind:     hidden_global_offset_x
      - .offset:         264
        .size:           8
        .value_kind:     hidden_global_offset_y
      - .offset:         272
        .size:           8
        .value_kind:     hidden_global_offset_z
      - .offset:         280
        .size:           2
        .value_kind:     hidden_grid_dims
      - .offset:         304
        .size:           8
        .value_kind:     hidden_multigrid_sync_arg
      - .offset:         336
        .size:           4
        .value_kind:     hidden_dynamic_lds_size
    .group_segment_fixed_size: 0
    .kernarg_segment_align: 8
    .kernarg_segment_size: 472
    .language:       OpenCL C
    .language_version:
      - 2
      - 0
    .max_flat_workgroup_size: 512
    .name:           _ZN2mk10fwd_kernelENS_6ParamsE
    .private_segment_fixed_size: 0
    .sgpr_count:     106
    .sgpr_spill_count: 0
    .symbol:         _ZN2mk10fwd_kernelENS_6ParamsE.kd
    .uniform_work_group_size: 1
    .uses_dynamic_stack: false
    .vgpr_count:     256
    .vgpr_spill_count: 0
    .wavefront_size: 64
